# MLA x-tile loop software-pipelined: QK(t+1) MFMAs overlap softmax(t), single staging set, max3 lane-local max
# speedup vs baseline: 1.0193x; 1.0193x over previous
.LBB0_6:
	s_add_u32 s4, s20, 0x7000
	s_addc_u32 s5, s21, 0
	v_writelane_b32 v246, s4, 5
	s_load_dwordx16 s[56:71], s[0:1], 0x0
	s_load_dwordx16 s[80:95], s[0:1], 0x40
	v_writelane_b32 v246, s5, 6
	s_add_u32 s4, s22, 0x7000
	s_addc_u32 s5, s23, 0
	v_writelane_b32 v246, s4, 7
	s_lshl_b32 s44, s10, 3
	s_lshl_b32 s72, s10, 8
	v_writelane_b32 v246, s5, 8
	s_mul_i32 s0, s11, s10
	v_readlane_b32 s38, v246, 0
	s_lshl_b32 s1, s38, 3
	v_writelane_b32 v246, s1, 9
	s_lshl_b32 s1, s38, 8
	s_cmpk_lt_i32 s38, 0x300
	v_writelane_b32 v246, s1, 10
	s_cselect_b64 s[4:5], -1, 0
	v_writelane_b32 v246, s4, 11
	s_cmpk_lt_i32 s38, 0xe10
	v_lshrrev_b32_e32 v1, 20, v0
	v_writelane_b32 v246, s5, 12
	s_cselect_b64 s[4:5], -1, 0
	v_writelane_b32 v246, s4, 13
	s_cmpk_lt_i32 s38, 0x60
	v_lshrrev_b32_e32 v0, 10, v0
	v_writelane_b32 v246, s5, 14
	s_cselect_b64 s[4:5], -1, 0
	s_waitcnt lgkmcnt(0)
	s_cmp_lg_u64 s[84:85], 0
	v_writelane_b32 v246, s4, 15
	s_cselect_b64 s[74:75], -1, 0
	s_cmpk_lt_i32 s38, 0x80
	v_writelane_b32 v246, s5, 16
	s_cselect_b64 s[4:5], -1, 0
	v_writelane_b32 v246, s4, 17
	s_cmp_lg_u64 s[88:89], 0
	v_or_b32_e32 v0, v0, v1
	v_writelane_b32 v246, s5, 18
	s_cselect_b64 s[4:5], -1, 0
	v_writelane_b32 v246, s4, 19
	s_cmpk_lt_i32 s38, 0x100
	s_mul_i32 s0, s0, s8
	v_writelane_b32 v246, s5, 20
	s_cselect_b64 s[4:5], -1, 0
	v_writelane_b32 v246, s4, 21
	s_cmpk_lt_i32 s38, 0x200
	v_mov_b32_e32 v1, 0
	v_writelane_b32 v246, s5, 22
	s_cselect_b64 s[4:5], -1, 0
	v_writelane_b32 v246, s4, 23
	s_cmpk_lt_i32 s38, 0x800
	s_movk_i32 s79, 0x100
	v_writelane_b32 v246, s5, 24
	s_cselect_b64 s[4:5], -1, 0
	s_and_b32 s29, s38, 7
	s_sub_i32 s1, s10, s29
	s_add_i32 s1, s1, 7
	v_writelane_b32 v246, s4, 25
	s_ashr_i32 s1, s1, 3
	s_ashr_i32 s30, s38, 3
	v_writelane_b32 v246, s5, 26
	s_cmpk_lt_i32 s30, 0x90
	v_writelane_b32 v246, s1, 27
	s_cselect_b64 s[4:5], -1, 0
	v_writelane_b32 v246, s4, 28
	s_cmpk_gt_i32 s30, 0x7f
	s_mov_b32 s9, 0
	v_writelane_b32 v246, s5, 29
	s_cselect_b64 s[4:5], -1, 0
	s_lshl_b32 s1, s38, 2
	v_writelane_b32 v246, s4, 30
	s_and_b32 s1, s1, 0x3e0
	s_bitset1_b32 s1, 14
	v_writelane_b32 v246, s5, 31
	v_writelane_b32 v246, s1, 32
	s_ashr_i32 s1, s38, 31
	s_lshr_b32 s1, s1, 25
	s_add_i32 s1, s30, s1
	s_ashr_i32 s4, s1, 7
	s_and_b32 s1, s1, 0x1ffff80
	s_sub_i32 s1, s30, s1
	s_and_b32 s1, s1, 0x1fffff8
	s_or_b32 s1, s1, s29
	s_lshl_b32 s31, s1, 7
	s_lshl_b32 s1, s4, 3
	s_and_b32 s4, s30, 7
	s_or_b32 s1, s1, s4
	s_or_b32 s33, s29, 0xfffffc00
	s_cmpk_lt_i32 s30, 0x240
	s_cselect_b64 s[4:5], -1, 0
	v_writelane_b32 v246, s4, 33
	s_cmpk_gt_i32 s30, 0x1ff
	s_mov_b64 s[36:37], 0x80
	v_writelane_b32 v246, s5, 34
	s_cselect_b64 s[4:5], -1, 0
	v_writelane_b32 v246, s4, 35
	s_mov_b32 s78, 0x800000
	s_mov_b64 s[46:47], 0xfa40080
	v_writelane_b32 v246, s5, 36
	s_add_i32 s4, s38, 0xf000
	s_and_b32 s4, s4, 0xffe0
	s_addk_i32 s4, 0x4000
	v_writelane_b32 v246, s4, 37
	s_and_b32 s4, s38, 31
	s_or_b32 s5, s29, 0xfffff000
	s_cmpk_lt_i32 s38, 0x420
	v_writelane_b32 v246, s5, 38
	s_cselect_b64 s[6:7], -1, 0
	s_not_b32 s5, s38
	v_writelane_b32 v246, s6, 39
	s_add_i32 s5, s10, s5
	s_cmp_lt_i32 s5, 64
	v_writelane_b32 v246, s7, 40
	v_writelane_b32 v246, s5, 41
	s_cselect_b64 s[6:7], -1, 0
	v_writelane_b32 v246, s6, 42
	s_cmp_lt_i32 s30, 64
	s_mov_b64 s[48:49], 0xfa48080
	v_writelane_b32 v246, s7, 43
	s_cselect_b64 s[6:7], -1, 0
	v_writelane_b32 v246, s6, 44
	s_cmpk_lt_i32 s38, 0x738
	s_mov_b64 s[50:51], 0xfa50080
	v_writelane_b32 v246, s7, 45
	s_cselect_b64 s[6:7], -1, 0
	v_writelane_b32 v246, s6, 46
	s_cmpk_gt_i32 s38, 0x317
	s_mov_b64 s[52:53], 0xfa58080
	v_writelane_b32 v246, s7, 47
	s_cselect_b64 s[6:7], -1, 0
	v_writelane_b32 v246, s6, 48
	s_add_i32 s5, s38, 0xfce8
	v_mov_b32_e32 v214, 0x3ecc95a3
	v_writelane_b32 v246, s7, 49
	s_and_b32 s6, s5, 0xffff
	s_mul_i32 s6, s6, 0xf83f
	s_lshr_b32 s7, s6, 16
	s_lshr_b32 s6, s6, 23
	s_mulk_i32 s6, 0x84
	s_sub_i32 s5, s5, s6
	s_lshl_b32 s5, s5, 7
	s_and_b32 s5, s5, 0xff80
	v_writelane_b32 v246, s5, 50
	s_and_b32 s5, s7, 0xff80
	v_writelane_b32 v246, s5, 51
	s_mul_hi_i32 s5, s38, 0x3e0f83e1
	s_lshr_b32 s6, s5, 31
	s_ashr_i32 s5, s5, 5
	s_add_i32 s5, s5, s6
	s_mul_i32 s6, s5, 0x84
	s_sub_i32 s6, s38, s6
	s_lshl_b32 s6, s6, 7
	s_lshl_b32 s5, s5, 7
	v_writelane_b32 v246, s6, 52
	s_cmpk_lt_i32 s38, 0x948
	v_writelane_b32 v246, s5, 53
	s_cselect_b64 s[6:7], -1, 0
	s_xor_b32 s5, s29, 4
	s_addk_i32 s5, 0xe4
	s_lshr_b32 s5, s5, 3
	v_writelane_b32 v246, s6, 54
	s_addk_i32 s5, 0x390
	s_cmp_lt_i32 s30, s5
	v_writelane_b32 v246, s7, 55
	v_writelane_b32 v246, s5, 56
	s_cselect_b64 s[6:7], -1, 0
	v_writelane_b32 v246, s6, 57
	s_xor_b32 s5, s38, 0xff80
	s_lshl_b32 s11, s29, 7
	v_writelane_b32 v246, s7, 58
	s_and_b32 s6, s5, 0xff
	s_mul_i32 s6, s6, 9
	s_bfe_u32 s6, s6, 0x70009
	s_lshl_b32 s7, s6, 7
	s_mul_i32 s6, s6, 57
	s_sub_i32 s5, s5, s6
	s_lshl_b32 s6, s30, 10
	s_or_b32 s34, s29, 0xffffe380
	s_or_b32 s6, s6, s11
	v_writelane_b32 v246, s34, 59
	s_bitset1_b32 s7, 14
	s_and_b32 s5, s5, 0xff
	s_add_i32 s6, s6, 0xfff20000
	v_writelane_b32 v246, s11, 60
	s_or_b32 s11, s11, 0xfff20000
	s_cmp_lt_i32 s96, 0
	v_writelane_b32 v246, s11, 61
	s_cselect_b64 s[34:35], -1, 0
	v_writelane_b32 v246, s34, 62
	v_mov_b32_e32 v162, 0x3727c5ac
	v_mov_b32_e32 v215, 0x1020c
	v_writelane_b32 v246, s35, 63
	s_add_u32 s34, s26, 0x19dce200
	s_addc_u32 s35, s27, 0
	v_writelane_b32 v245, s34, 0
	s_mov_b32 s76, 0x7f61b1e6
	s_mov_b32 s77, 0x41000000
	v_writelane_b32 v245, s35, 1
	s_add_u32 s34, s26, 0x19dce400
	s_addc_u32 s35, s27, 0
	v_writelane_b32 v245, s34, 2
	s_mov_b64 s[54:55], 0x1c8000
	v_mov_b32_e32 v216, 0x3e91f4c4
	v_writelane_b32 v245, s35, 3
	s_add_u32 s34, s26, 0x19dce500
	s_addc_u32 s35, s27, 0
	v_writelane_b32 v245, s34, 4
	v_mov_b32_e32 v217, 0x204
	v_mov_b32_e32 v218, 0x3c0881c4
	v_writelane_b32 v245, s35, 5
	s_add_u32 s34, s26, 0x19dce600
	s_addc_u32 s35, s27, 0
	v_writelane_b32 v245, s34, 6
	v_mov_b32_e32 v219, 0xbab64f3b
	v_mov_b32_e32 v220, 0x10200
	v_writelane_b32 v245, s35, 7
	s_add_u32 s34, s26, 0x19dce700
	s_addc_u32 s35, s27, 0
	v_writelane_b32 v245, s34, 8
	v_mov_b32_e32 v221, 0x10204
	v_mov_b32_e32 v222, 1
	v_writelane_b32 v245, s35, 9
	s_add_u32 s34, s26, 0x19dce800
	s_addc_u32 s35, s27, 0
	v_writelane_b32 v245, s34, 10
	v_mov_b32_e32 v223, 0x7f800000
	v_mov_b32_e32 v224, 0x7fc00000
	v_writelane_b32 v245, s35, 11
	s_add_u32 s34, s26, 0x19dce900
	s_addc_u32 s35, s27, 0
	v_writelane_b32 v245, s34, 12
	v_mov_b32_e32 v225, 0xff800000
	v_mov_b32_e32 v226, 0x8000
	v_writelane_b32 v245, s35, 13
	s_add_u32 s34, s26, 0x19dcea00
	s_addc_u32 s35, s27, 0
	v_writelane_b32 v245, s34, 14
	v_mov_b32_e32 v227, 0x3900
	v_mov_b32_e32 v228, 0xf149f2ca
	v_writelane_b32 v245, s35, 15
	s_add_u32 s34, s26, 0x19dceb00
	s_addc_u32 s35, s27, 0
	v_writelane_b32 v245, s34, 16
	v_mov_b32_e32 v229, 0x42800000
	v_not_b32_e32 v230, 63
	v_writelane_b32 v245, s35, 17
	s_add_u32 s34, s26, 0x19dcec00
	s_addc_u32 s35, s27, 0
	v_writelane_b32 v245, s34, 18
	v_mov_b32_e32 v231, 0x10000
	v_mov_b32_e32 v236, v1
	v_writelane_b32 v245, s35, 19
	s_add_u32 s34, s26, 0x19dced00
	s_addc_u32 s35, s27, 0
	v_writelane_b32 v245, s34, 20
	v_mov_b32_e32 v237, v1
	v_mov_b32_e32 v238, v1
	v_writelane_b32 v245, s35, 21
	s_add_u32 s34, s26, 0x19dcee00
	s_addc_u32 s35, s27, 0
	v_writelane_b32 v245, s34, 22
	v_mov_b32_e32 v239, v1
	v_mov_b32_e32 v232, 0x461c4000
	v_writelane_b32 v245, s35, 23
	s_add_u32 s34, s26, 0x19dcef00
	s_addc_u32 s35, s27, 0
	v_writelane_b32 v245, s34, 24
	v_mov_b32_e32 v233, 0x37000000
	v_not_b32_e32 v234, 31
	v_writelane_b32 v245, s35, 25
	s_add_u32 s34, s26, 0x19dcf000
	s_addc_u32 s35, s27, 0
	v_writelane_b32 v245, s34, 26
	s_nop 1
	v_writelane_b32 v245, s35, 27
	s_add_u32 s34, s26, 0x19dcf100
	s_addc_u32 s35, s27, 0
	v_writelane_b32 v245, s34, 28
	s_nop 1
	v_writelane_b32 v245, s35, 29
	s_add_u32 s34, s26, 0x19dcf200
	s_addc_u32 s35, s27, 0
	v_writelane_b32 v245, s34, 30
	s_nop 1
	v_writelane_b32 v245, s35, 31
	s_add_u32 s34, s26, 0x19dcf300
	s_addc_u32 s35, s27, 0
	v_writelane_b32 v245, s34, 32
	s_cmp_eq_u32 s28, 15
	s_nop 0
	v_writelane_b32 v245, s35, 33
	s_cselect_b64 s[34:35], -1, 0
	v_writelane_b32 v245, s34, 34
	s_cmp_eq_u32 s28, 14
	s_nop 0
	v_writelane_b32 v245, s35, 35
	s_cselect_b64 s[34:35], -1, 0
	v_writelane_b32 v245, s34, 36
	s_cmp_eq_u32 s28, 13
	s_nop 0
	v_writelane_b32 v245, s35, 37
	s_cselect_b64 s[34:35], -1, 0
	v_writelane_b32 v245, s34, 38
	s_cmp_eq_u32 s28, 12
	s_nop 0
	v_writelane_b32 v245, s35, 39
	s_cselect_b64 s[34:35], -1, 0
	v_writelane_b32 v245, s34, 40
	s_cmp_eq_u32 s28, 11
	s_nop 0
	v_writelane_b32 v245, s35, 41
	s_cselect_b64 s[34:35], -1, 0
	v_writelane_b32 v245, s34, 42
	s_cmp_eq_u32 s28, 10
	s_nop 0
	v_writelane_b32 v245, s35, 43
	s_cselect_b64 s[34:35], -1, 0
	v_writelane_b32 v245, s34, 44
	s_cmp_eq_u32 s28, 9
	s_nop 0
	v_writelane_b32 v245, s35, 45
	s_cselect_b64 s[34:35], -1, 0
	v_writelane_b32 v245, s34, 46
	s_cmp_eq_u32 s28, 8
	s_nop 0
	v_writelane_b32 v245, s35, 47
	s_cselect_b64 s[34:35], -1, 0
	v_writelane_b32 v245, s34, 48
	s_cmp_eq_u32 s28, 7
	s_nop 0
	v_writelane_b32 v245, s35, 49
	s_cselect_b64 s[34:35], -1, 0
	v_writelane_b32 v245, s34, 50
	s_cmp_eq_u32 s28, 6
	s_nop 0
	v_writelane_b32 v245, s35, 51
	s_cselect_b64 s[34:35], -1, 0
	v_writelane_b32 v245, s34, 52
	s_cmp_eq_u32 s28, 5
	s_nop 0
	v_writelane_b32 v245, s35, 53
	s_cselect_b64 s[34:35], -1, 0
	v_writelane_b32 v245, s34, 54
	s_cmp_eq_u32 s28, 4
	s_nop 0
	v_writelane_b32 v245, s35, 55
	s_cselect_b64 s[34:35], -1, 0
	v_writelane_b32 v245, s34, 56
	s_cmp_eq_u32 s28, 3
	s_nop 0
	v_writelane_b32 v245, s35, 57
	s_cselect_b64 s[34:35], -1, 0
	v_writelane_b32 v245, s34, 58
	s_cmp_eq_u32 s28, 2
	s_nop 0
	v_writelane_b32 v245, s35, 59
	s_cselect_b64 s[34:35], -1, 0
	v_writelane_b32 v245, s34, 60
	s_cmp_eq_u32 s28, 1
	s_nop 0
	v_writelane_b32 v245, s35, 61
	s_cselect_b64 s[34:35], -1, 0
	v_writelane_b32 v245, s34, 62
	s_cmp_eq_u32 s28, 0
	s_nop 0
	v_writelane_b32 v245, s35, 63
	s_cselect_b64 s[34:35], -1, 0
	s_lshl_b32 s11, s28, 8
	s_add_u32 s2, s2, s11
	v_writelane_b32 v244, s34, 0
	s_addc_u32 s3, s3, 0
	s_movk_i32 s11, 0x6000
	v_writelane_b32 v244, s35, 1
	s_add_u32 s34, s2, 0x1400
	s_addc_u32 s35, s3, 0
	v_writelane_b32 v244, s34, 2
	s_add_u32 s2, s2, 0x2400
	s_addc_u32 s3, s3, 0
	v_writelane_b32 v244, s35, 3
	v_writelane_b32 v244, s2, 4
	s_mov_b64 s[34:35], 0x40000
	s_mov_b32 s28, 0x3f803f80
	v_mov_b32_e32 v248, 0x3f803f80
	v_mov_b32_e32 v249, 0x3f803f80
	v_mov_b32_e32 v250, 0x3f803f80
	v_mov_b32_e32 v251, 0x3f803f80
	v_writelane_b32 v244, s3, 5
	s_add_u32 s2, s26, 0x19dd1400
	s_addc_u32 s3, s27, 0
	v_writelane_b32 v244, s2, 6
	s_nop 1
	v_writelane_b32 v244, s3, 7
	s_add_u32 s2, s26, 0x19dd1500
	s_addc_u32 s3, s27, 0
	v_writelane_b32 v244, s2, 8
	s_cmpk_lt_i32 s30, 0x80
	s_nop 0
	v_writelane_b32 v244, s3, 9
	s_cselect_b32 s2, s1, s29
	v_writelane_b32 v244, s29, 10
	s_lshl_b32 s2, s2, 7
	v_writelane_b32 v244, s2, 11
	s_lshl_b32 s2, s33, 2
	v_writelane_b32 v244, s33, 12
	s_cmpk_lt_i32 s30, 0x200
	v_writelane_b32 v244, s2, 13
	s_cselect_b32 s2, s1, s4
	s_lshl_b32 s2, s2, 7
	s_movk_i32 s4, 0x3ff
	v_writelane_b32 v244, s2, 14
	s_cmpk_lt_u32 s30, 0x390
	v_and_or_b32 v0, v0, s4, v163
	s_cselect_b32 s3, 56, s5
	v_writelane_b32 v244, s30, 15
	v_cmp_eq_u32_e64 s[4:5], 0, v0
	s_cselect_b32 s2, s6, s7
	s_cmpk_lt_i32 s30, 0x380
	v_writelane_b32 v244, s4, 16
	s_movk_i32 s33, 0x3900
	s_nop 0
	v_writelane_b32 v244, s5, 17
	v_writelane_b32 v244, s0, 18
	v_writelane_b32 v244, s31, 19
	s_cselect_b32 s0, s31, s2
	v_writelane_b32 v244, s0, 20
	s_cselect_b32 s0, s1, s3
	s_lshl_b32 s0, s0, 7
	v_writelane_b32 v244, s0, 21
	s_lshl_b32 s0, s38, 5
	v_writelane_b32 v244, s0, 22
	s_add_u32 s0, s26, 0xf930000
	v_writelane_b32 v244, s0, 23
	s_addc_u32 s0, s27, 0
	s_ashr_i32 s73, s72, 31
	s_lshl_b64 s[2:3], s[72:73], 4
	v_writelane_b32 v244, s0, 24
	s_add_u32 s0, s26, 0x80
	s_addc_u32 s1, s27, 0
	v_writelane_b32 v244, s0, 25
	s_nop 1
	v_writelane_b32 v244, s1, 26
	s_add_u32 s0, s26, 0x13240080
	v_writelane_b32 v244, s0, 27
	s_addc_u32 s0, s27, 0
	v_writelane_b32 v244, s0, 28
	s_add_u32 s0, s26, 0x13240800
	s_addc_u32 s1, s27, 0
	v_writelane_b32 v244, s0, 29
	s_ashr_i32 s45, s44, 31
	s_nop 0
	v_writelane_b32 v244, s1, 30
	s_lshl_b64 s[0:1], s[44:45], 11
	v_writelane_b32 v244, s0, 31
	s_bitcmp1_b32 s38, 0
	s_nop 0
	v_writelane_b32 v244, s1, 32
	s_cselect_b64 s[0:1], -1, 0
	v_writelane_b32 v244, s0, 33
	s_bitcmp1_b32 s10, 0
	s_nop 0
	v_writelane_b32 v244, s1, 34
	s_cselect_b64 s[0:1], -1, 0
	v_writelane_b32 v244, s0, 35
	s_nop 1
	v_writelane_b32 v244, s1, 36
	s_sub_i32 s0, s10, s38
	s_sub_i32 s0, s0, 33
	v_writelane_b32 v244, s0, 37
	s_add_u32 s0, s26, 0x11140800
	s_addc_u32 s1, s27, 0
	v_writelane_b32 v244, s0, 38
	s_nop 1
	v_writelane_b32 v244, s1, 39
	v_writelane_b32 v244, s56, 40
	s_mov_b32 s0, s44
	s_nop 0
	v_writelane_b32 v244, s57, 41
	v_writelane_b32 v244, s58, 42
	v_writelane_b32 v244, s59, 43
	v_writelane_b32 v244, s60, 44
	v_writelane_b32 v244, s61, 45
	v_writelane_b32 v244, s62, 46
	v_writelane_b32 v244, s63, 47
	v_writelane_b32 v244, s64, 48
	v_writelane_b32 v244, s65, 49
	v_writelane_b32 v244, s66, 50
	v_writelane_b32 v244, s67, 51
	v_writelane_b32 v244, s68, 52
	v_writelane_b32 v244, s69, 53
	v_writelane_b32 v244, s70, 54
	v_writelane_b32 v244, s71, 55
	v_writelane_b32 v244, s80, 56
	s_nop 1
	v_writelane_b32 v235, s88, 0
	v_writelane_b32 v235, s89, 1
	v_writelane_b32 v235, s90, 2
	v_writelane_b32 v235, s91, 3
	v_writelane_b32 v235, s92, 4
	v_writelane_b32 v235, s93, 5
	v_writelane_b32 v235, s94, 6
	v_writelane_b32 v235, s95, 7
	v_writelane_b32 v235, s0, 8
	v_writelane_b32 v244, s81, 57
	v_writelane_b32 v244, s82, 58
	v_writelane_b32 v235, s1, 9
	s_mov_b32 s0, s72
	v_writelane_b32 v235, s0, 10
	v_writelane_b32 v244, s83, 59
	v_writelane_b32 v244, s84, 60
	v_writelane_b32 v235, s1, 11
	v_writelane_b32 v235, s74, 12
	v_writelane_b32 v244, s85, 61
	v_writelane_b32 v244, s86, 62
	v_writelane_b32 v235, s75, 13
	v_writelane_b32 v235, s2, 14
	v_writelane_b32 v244, s87, 63
	s_nop 0
	v_writelane_b32 v235, s3, 15
	s_branch .LBB0_10

.Lmla_x_pro:
	s_waitcnt vmcnt(0)
	ds_write_b128 v168, v[56:59] offset:20480
	ds_write_b128 v168, v[60:63] offset:22528
	ds_write_b128 v169, v[52:55] offset:28672
	v_lshl_add_u64 v[164:165], s[26:27], 0, v[164:165]
	v_lshl_add_u64 v[160:161], s[26:27], 0, v[160:161]
	s_mov_b64 s[0:1], 0x14b40000
	v_lshl_add_u64 v[164:165], v[164:165], 0, s[0:1]
	s_mov_b64 s[0:1], 0x1cb800
	v_lshl_add_u64 v[160:161], v[160:161], 0, s[0:1]
	s_mov_b64 s[0:1], 0x10000
	v_lshl_add_u64 v[212:213], v[164:165], 0, s[0:1]
	global_load_dwordx4 v[56:59], v[164:165], off
	global_load_dwordx4 v[60:63], v[212:213], off
	global_load_dwordx4 v[52:55], v[160:161], off
	s_mov_b64 s[0:1], 0xe4000
	v_lshl_add_u64 v[160:161], v[160:161], 0, s[0:1]
	ds_read_b128 v[4:7], v175 offset:0
	ds_read_b128 v[12:15], v175 offset:4096
	ds_read_b128 v[20:23], v175 offset:8192
	s_waitcnt lgkmcnt(0)
	v_mfma_f32_16x16x32_bf16 v[116:119], v[4:7], v[8:11], v[108:111]
	v_mfma_f32_16x16x32_bf16 v[132:135], v[4:7], v[40:43], v[112:115]
	v_mfma_f32_16x16x32_bf16 v[116:119], v[12:15], v[32:35], v[116:119]
	v_mfma_f32_16x16x32_bf16 v[132:135], v[12:15], v[44:47], v[132:135]
	v_mfma_f32_16x16x32_bf16 v[116:119], v[20:23], v[36:39], v[116:119]
	v_mfma_f32_16x16x32_bf16 v[132:135], v[20:23], v[16:19], v[132:135]
	ds_read_b128 v[4:7], v175 offset:1024
	ds_read_b128 v[12:15], v175 offset:5120
	ds_read_b128 v[20:23], v175 offset:9216
	s_waitcnt lgkmcnt(0)
	v_mfma_f32_16x16x32_bf16 v[120:123], v[4:7], v[8:11], v[108:111]
	v_mfma_f32_16x16x32_bf16 v[136:139], v[4:7], v[40:43], v[112:115]
	v_mfma_f32_16x16x32_bf16 v[120:123], v[12:15], v[32:35], v[120:123]
	v_mfma_f32_16x16x32_bf16 v[136:139], v[12:15], v[44:47], v[136:139]
	v_mfma_f32_16x16x32_bf16 v[120:123], v[20:23], v[36:39], v[120:123]
	v_mfma_f32_16x16x32_bf16 v[136:139], v[20:23], v[16:19], v[136:139]
	ds_read_b128 v[4:7], v175 offset:2048
	ds_read_b128 v[12:15], v175 offset:6144
	ds_read_b128 v[20:23], v175 offset:10240
	s_waitcnt lgkmcnt(0)
	v_mfma_f32_16x16x32_bf16 v[124:127], v[4:7], v[8:11], v[108:111]
	v_mfma_f32_16x16x32_bf16 v[140:143], v[4:7], v[40:43], v[112:115]
	v_mfma_f32_16x16x32_bf16 v[124:127], v[12:15], v[32:35], v[124:127]
	v_mfma_f32_16x16x32_bf16 v[140:143], v[12:15], v[44:47], v[140:143]
	v_mfma_f32_16x16x32_bf16 v[124:127], v[20:23], v[36:39], v[124:127]
	v_mfma_f32_16x16x32_bf16 v[140:143], v[20:23], v[16:19], v[140:143]
	ds_read_b128 v[4:7], v175 offset:3072
	ds_read_b128 v[12:15], v175 offset:7168
	ds_read_b128 v[20:23], v175 offset:11264
	s_waitcnt lgkmcnt(0)
	v_mfma_f32_16x16x32_bf16 v[128:131], v[4:7], v[8:11], v[108:111]
	v_mfma_f32_16x16x32_bf16 v[144:147], v[4:7], v[40:43], v[112:115]
	v_mfma_f32_16x16x32_bf16 v[128:131], v[12:15], v[32:35], v[128:131]
	v_mfma_f32_16x16x32_bf16 v[144:147], v[12:15], v[44:47], v[144:147]
	v_mfma_f32_16x16x32_bf16 v[128:131], v[20:23], v[36:39], v[128:131]
	v_mfma_f32_16x16x32_bf16 v[144:147], v[20:23], v[16:19], v[144:147]
	s_waitcnt lgkmcnt(0)
	s_barrier
.Lmla_x_body0:
	s_waitcnt vmcnt(0)
	ds_write_b128 v168, v[56:59] offset:0
	ds_write_b128 v168, v[60:63] offset:2048
	ds_write_b128 v169, v[52:55] offset:8192
	ds_write_b128 v170, v[48:51] offset:32768
	ds_write_b128 v170, v[64:67] offset:36864
	ds_read_b128 v[4:7], v175 offset:20480
	ds_read_b128 v[12:15], v175 offset:24576
	ds_read_b128 v[20:23], v175 offset:28672
	ds_read_b64_tr_b16 v[24:25], v167 offset:12288
	ds_read_b64_tr_b16 v[26:27], v167 offset:14336
	ds_read_b64_tr_b16 v[28:29], v171 offset:12288
	ds_read_b64_tr_b16 v[30:31], v171 offset:14336
	ds_read_b64_tr_b16 v[148:149], v172 offset:12288
	ds_read_b64_tr_b16 v[150:151], v172 offset:14336
	ds_read_b64_tr_b16 v[152:153], v173 offset:12288
	ds_read_b64_tr_b16 v[154:155], v173 offset:14336
	global_load_dwordx4 v[48:51], v[164:165], off offset:128
	s_mov_b64 s[0:1], 0x10000
	v_lshl_add_u64 v[212:213], v[164:165], 0, s[0:1]
	global_load_dwordx4 v[64:67], v[212:213], off offset:128
	s_mov_b64 s[0:1], 0x20000
	v_lshl_add_u64 v[164:165], v[164:165], 0, s[0:1]
	global_load_dwordx4 v[56:59], v[164:165], off
	s_mov_b64 s[0:1], 0x10000
	v_lshl_add_u64 v[212:213], v[164:165], 0, s[0:1]
	global_load_dwordx4 v[60:63], v[212:213], off
	global_load_dwordx4 v[52:55], v[160:161], off
	s_mov_b64 s[0:1], 0xe4000
	v_lshl_add_u64 v[160:161], v[160:161], 0, s[0:1]
	v_max3_f32 v2, v116, v117, v118
	v_max3_f32 v3, v132, v133, v134
	v_max3_f32 v2, v2, v119, v120
	v_max3_f32 v3, v3, v135, v136
	v_max3_f32 v2, v2, v121, v122
	v_max3_f32 v3, v3, v137, v138
	v_max3_f32 v2, v2, v123, v124
	v_max3_f32 v3, v3, v139, v140
	v_max3_f32 v2, v2, v125, v126
	v_max3_f32 v3, v3, v141, v142
	v_max3_f32 v2, v2, v127, v128
	v_max3_f32 v3, v3, v143, v144
	v_max3_f32 v2, v2, v129, v130
	v_max3_f32 v3, v3, v145, v146
	v_max3_f32 v2, v2, v131, v131
	v_max3_f32 v3, v3, v147, v147
	v_cmp_lt_f32_e32 vcc, s77, v2
	v_cmp_lt_f32_e64 s[2:3], s77, v3
	s_cmp_eq_u32 s57, 0
	s_cselect_b64 s[0:1], -1, 0
	s_or_b64 s[2:3], s[2:3], vcc
	s_or_b64 s[2:3], s[2:3], s[0:1]
	s_cbranch_scc1 .Lmla_x_rare0
.Lmla_x_cont0:
	s_waitcnt lgkmcnt(8)
	v_exp_f32_e32 v116, v116
	v_mfma_f32_16x16x32_bf16 v[176:179], v[4:7], v[8:11], v[108:111]
	v_exp_f32_e32 v117, v117
	v_mfma_f32_16x16x32_bf16 v[192:195], v[4:7], v[40:43], v[112:115]
	v_exp_f32_e32 v118, v118
	v_mfma_f32_16x16x32_bf16 v[176:179], v[12:15], v[32:35], v[176:179]
	v_exp_f32_e32 v119, v119
	v_mfma_f32_16x16x32_bf16 v[192:195], v[12:15], v[44:47], v[192:195]
	v_exp_f32_e32 v132, v132
	v_mfma_f32_16x16x32_bf16 v[176:179], v[20:23], v[36:39], v[176:179]
	v_exp_f32_e32 v133, v133
	v_mfma_f32_16x16x32_bf16 v[192:195], v[20:23], v[16:19], v[192:195]
	v_exp_f32_e32 v134, v134
	v_exp_f32_e32 v135, v135
	ds_read_b128 v[4:7], v175 offset:21504
	ds_read_b128 v[12:15], v175 offset:25600
	ds_read_b128 v[20:23], v175 offset:29696
	v_exp_f32_e32 v120, v120
	v_exp_f32_e32 v121, v121
	v_exp_f32_e32 v122, v122
	v_exp_f32_e32 v123, v123
	v_exp_f32_e32 v136, v136
	v_exp_f32_e32 v137, v137
	v_exp_f32_e32 v138, v138
	v_exp_f32_e32 v139, v139
	s_nop 0
	v_cvt_pk_bf16_f32 v116, v116, v117
	v_cvt_pk_bf16_f32 v117, v118, v119
	v_cvt_pk_bf16_f32 v118, v120, v121
	v_cvt_pk_bf16_f32 v119, v122, v123
	v_cvt_pk_bf16_f32 v132, v132, v133
	v_cvt_pk_bf16_f32 v133, v134, v135
	v_cvt_pk_bf16_f32 v134, v136, v137
	v_cvt_pk_bf16_f32 v135, v138, v139
	s_waitcnt lgkmcnt(0)
	v_exp_f32_e32 v124, v124
	v_mfma_f32_16x16x32_bf16 v[180:183], v[4:7], v[8:11], v[108:111]
	v_exp_f32_e32 v125, v125
	v_mfma_f32_16x16x32_bf16 v[196:199], v[4:7], v[40:43], v[112:115]
	v_exp_f32_e32 v126, v126
	v_mfma_f32_16x16x32_bf16 v[180:183], v[12:15], v[32:35], v[180:183]
	v_exp_f32_e32 v127, v127
	v_mfma_f32_16x16x32_bf16 v[196:199], v[12:15], v[44:47], v[196:199]
	v_exp_f32_e32 v140, v140
	v_mfma_f32_16x16x32_bf16 v[180:183], v[20:23], v[36:39], v[180:183]
	v_exp_f32_e32 v141, v141
	v_mfma_f32_16x16x32_bf16 v[196:199], v[20:23], v[16:19], v[196:199]
	v_exp_f32_e32 v142, v142
	v_exp_f32_e32 v143, v143
	ds_read_b128 v[4:7], v175 offset:22528
	ds_read_b128 v[12:15], v175 offset:26624
	ds_read_b128 v[20:23], v175 offset:30720
	ds_read_b64_tr_b16 v[208:209], v167 offset:16384
	ds_read_b64_tr_b16 v[210:211], v167 offset:18432
	ds_read_b64_tr_b16 v[240:241], v171 offset:16384
	ds_read_b64_tr_b16 v[242:243], v171 offset:18432
	ds_read_b64_tr_b16 v[252:253], v172 offset:16384
	ds_read_b64_tr_b16 v[254:255], v172 offset:18432
	v_mfma_f32_16x16x32_bf16 v[104:107], v[248:251], v[116:119], v[104:107]
	v_exp_f32_e32 v128, v128
	v_mfma_f32_16x16x32_bf16 v[88:91], v[248:251], v[132:135], v[88:91]
	v_exp_f32_e32 v129, v129
	v_mfma_f32_16x16x32_bf16 v[100:103], v[24:27], v[116:119], v[100:103]
	v_exp_f32_e32 v130, v130
	v_mfma_f32_16x16x32_bf16 v[80:83], v[24:27], v[132:135], v[80:83]
	v_exp_f32_e32 v131, v131
	v_mfma_f32_16x16x32_bf16 v[96:99], v[28:31], v[116:119], v[96:99]
	v_exp_f32_e32 v144, v144
	v_mfma_f32_16x16x32_bf16 v[76:79], v[28:31], v[132:135], v[76:79]
	v_exp_f32_e32 v145, v145
	v_mfma_f32_16x16x32_bf16 v[92:95], v[148:151], v[116:119], v[92:95]
	v_exp_f32_e32 v146, v146
	v_mfma_f32_16x16x32_bf16 v[72:75], v[148:151], v[132:135], v[72:75]
	v_exp_f32_e32 v147, v147
	v_mfma_f32_16x16x32_bf16 v[84:87], v[152:155], v[116:119], v[84:87]
	v_mfma_f32_16x16x32_bf16 v[68:71], v[152:155], v[132:135], v[68:71]
	s_waitcnt lgkmcnt(6)
	v_mfma_f32_16x16x32_bf16 v[184:187], v[4:7], v[8:11], v[108:111]
	v_cvt_pk_bf16_f32 v124, v124, v125
	v_cvt_pk_bf16_f32 v125, v126, v127
	v_mfma_f32_16x16x32_bf16 v[200:203], v[4:7], v[40:43], v[112:115]
	v_cvt_pk_bf16_f32 v126, v128, v129
	v_cvt_pk_bf16_f32 v127, v130, v131
	v_mfma_f32_16x16x32_bf16 v[184:187], v[12:15], v[32:35], v[184:187]
	v_cvt_pk_bf16_f32 v140, v140, v141
	v_cvt_pk_bf16_f32 v141, v142, v143
	v_mfma_f32_16x16x32_bf16 v[200:203], v[12:15], v[44:47], v[200:203]
	v_cvt_pk_bf16_f32 v142, v144, v145
	v_cvt_pk_bf16_f32 v143, v146, v147
	v_mfma_f32_16x16x32_bf16 v[184:187], v[20:23], v[36:39], v[184:187]
	v_mfma_f32_16x16x32_bf16 v[200:203], v[20:23], v[16:19], v[200:203]
	ds_read_b128 v[4:7], v175 offset:23552
	ds_read_b128 v[12:15], v175 offset:27648
	ds_read_b128 v[20:23], v175 offset:31744
	ds_read_b64_tr_b16 v[24:25], v173 offset:16384
	ds_read_b64_tr_b16 v[26:27], v173 offset:18432
	s_waitcnt lgkmcnt(5)
	v_mfma_f32_16x16x32_bf16 v[104:107], v[248:251], v[124:127], v[104:107]
	v_mfma_f32_16x16x32_bf16 v[88:91], v[248:251], v[140:143], v[88:91]
	v_mfma_f32_16x16x32_bf16 v[100:103], v[208:211], v[124:127], v[100:103]
	v_mfma_f32_16x16x32_bf16 v[80:83], v[208:211], v[140:143], v[80:83]
	v_mfma_f32_16x16x32_bf16 v[96:99], v[240:243], v[124:127], v[96:99]
	v_mfma_f32_16x16x32_bf16 v[76:79], v[240:243], v[140:143], v[76:79]
	v_mfma_f32_16x16x32_bf16 v[92:95], v[252:255], v[124:127], v[92:95]
	v_mfma_f32_16x16x32_bf16 v[72:75], v[252:255], v[140:143], v[72:75]
	s_waitcnt lgkmcnt(2)
	v_mfma_f32_16x16x32_bf16 v[188:191], v[4:7], v[8:11], v[108:111]
	v_mfma_f32_16x16x32_bf16 v[204:207], v[4:7], v[40:43], v[112:115]
	v_mfma_f32_16x16x32_bf16 v[188:191], v[12:15], v[32:35], v[188:191]
	v_mfma_f32_16x16x32_bf16 v[204:207], v[12:15], v[44:47], v[204:207]
	v_mfma_f32_16x16x32_bf16 v[188:191], v[20:23], v[36:39], v[188:191]
	v_mfma_f32_16x16x32_bf16 v[204:207], v[20:23], v[16:19], v[204:207]
	s_waitcnt lgkmcnt(0)
	v_mfma_f32_16x16x32_bf16 v[84:87], v[24:27], v[124:127], v[84:87]
	v_mfma_f32_16x16x32_bf16 v[68:71], v[24:27], v[140:143], v[68:71]
	s_add_i32 s57, s57, 1
	s_cmp_lt_u32 s57, s44
	s_barrier
	s_cbranch_scc0 .Lmla_x_done
.Lmla_x_body1:
	s_waitcnt vmcnt(0)
	ds_write_b128 v168, v[56:59] offset:20480
	ds_write_b128 v168, v[60:63] offset:22528
	ds_write_b128 v169, v[52:55] offset:28672
	ds_write_b128 v170, v[48:51] offset:12288
	ds_write_b128 v170, v[64:67] offset:16384
	ds_read_b128 v[4:7], v175 offset:0
	ds_read_b128 v[12:15], v175 offset:4096
	ds_read_b128 v[20:23], v175 offset:8192
	ds_read_b64_tr_b16 v[24:25], v167 offset:32768
	ds_read_b64_tr_b16 v[26:27], v167 offset:34816
	ds_read_b64_tr_b16 v[28:29], v171 offset:32768
	ds_read_b64_tr_b16 v[30:31], v171 offset:34816
	ds_read_b64_tr_b16 v[148:149], v172 offset:32768
	ds_read_b64_tr_b16 v[150:151], v172 offset:34816
	ds_read_b64_tr_b16 v[152:153], v173 offset:32768
	ds_read_b64_tr_b16 v[154:155], v173 offset:34816
	global_load_dwordx4 v[48:51], v[164:165], off offset:128
	s_mov_b64 s[0:1], 0x10000
	v_lshl_add_u64 v[212:213], v[164:165], 0, s[0:1]
	global_load_dwordx4 v[64:67], v[212:213], off offset:128
	s_mov_b64 s[0:1], 0x20000
	v_lshl_add_u64 v[164:165], v[164:165], 0, s[0:1]
	global_load_dwordx4 v[56:59], v[164:165], off
	s_mov_b64 s[0:1], 0x10000
	v_lshl_add_u64 v[212:213], v[164:165], 0, s[0:1]
	global_load_dwordx4 v[60:63], v[212:213], off
	global_load_dwordx4 v[52:55], v[160:161], off
	s_mov_b64 s[0:1], 0xe4000
	v_lshl_add_u64 v[160:161], v[160:161], 0, s[0:1]
	v_max3_f32 v2, v176, v177, v178
	v_max3_f32 v3, v192, v193, v194
	v_max3_f32 v2, v2, v179, v180
	v_max3_f32 v3, v3, v195, v196
	v_max3_f32 v2, v2, v181, v182
	v_max3_f32 v3, v3, v197, v198
	v_max3_f32 v2, v2, v183, v184
	v_max3_f32 v3, v3, v199, v200
	v_max3_f32 v2, v2, v185, v186
	v_max3_f32 v3, v3, v201, v202
	v_max3_f32 v2, v2, v187, v188
	v_max3_f32 v3, v3, v203, v204
	v_max3_f32 v2, v2, v189, v190
	v_max3_f32 v3, v3, v205, v206
	v_max3_f32 v2, v2, v191, v191
	v_max3_f32 v3, v3, v207, v207
	v_cmp_lt_f32_e32 vcc, s77, v2
	v_cmp_lt_f32_e64 s[2:3], s77, v3
	s_cmp_eq_u32 s57, 0
	s_cselect_b64 s[0:1], -1, 0
	s_or_b64 s[2:3], s[2:3], vcc
	s_or_b64 s[2:3], s[2:3], s[0:1]
	s_cbranch_scc1 .Lmla_x_rare1
.Lmla_x_cont1:
	s_waitcnt lgkmcnt(8)
	v_exp_f32_e32 v176, v176
	v_mfma_f32_16x16x32_bf16 v[116:119], v[4:7], v[8:11], v[108:111]
	v_exp_f32_e32 v177, v177
	v_mfma_f32_16x16x32_bf16 v[132:135], v[4:7], v[40:43], v[112:115]
	v_exp_f32_e32 v178, v178
	v_mfma_f32_16x16x32_bf16 v[116:119], v[12:15], v[32:35], v[116:119]
	v_exp_f32_e32 v179, v179
	v_mfma_f32_16x16x32_bf16 v[132:135], v[12:15], v[44:47], v[132:135]
	v_exp_f32_e32 v192, v192
	v_mfma_f32_16x16x32_bf16 v[116:119], v[20:23], v[36:39], v[116:119]
	v_exp_f32_e32 v193, v193
	v_mfma_f32_16x16x32_bf16 v[132:135], v[20:23], v[16:19], v[132:135]
	v_exp_f32_e32 v194, v194
	v_exp_f32_e32 v195, v195
	ds_read_b128 v[4:7], v175 offset:1024
	ds_read_b128 v[12:15], v175 offset:5120
	ds_read_b128 v[20:23], v175 offset:9216
	v_exp_f32_e32 v180, v180
	v_exp_f32_e32 v181, v181
	v_exp_f32_e32 v182, v182
	v_exp_f32_e32 v183, v183
	v_exp_f32_e32 v196, v196
	v_exp_f32_e32 v197, v197
	v_exp_f32_e32 v198, v198
	v_exp_f32_e32 v199, v199
	s_nop 0
	v_cvt_pk_bf16_f32 v176, v176, v177
	v_cvt_pk_bf16_f32 v177, v178, v179
	v_cvt_pk_bf16_f32 v178, v180, v181
	v_cvt_pk_bf16_f32 v179, v182, v183
	v_cvt_pk_bf16_f32 v192, v192, v193
	v_cvt_pk_bf16_f32 v193, v194, v195
	v_cvt_pk_bf16_f32 v194, v196, v197
	v_cvt_pk_bf16_f32 v195, v198, v199
	s_waitcnt lgkmcnt(0)
	v_exp_f32_e32 v184, v184
	v_mfma_f32_16x16x32_bf16 v[120:123], v[4:7], v[8:11], v[108:111]
	v_exp_f32_e32 v185, v185
	v_mfma_f32_16x16x32_bf16 v[136:139], v[4:7], v[40:43], v[112:115]
	v_exp_f32_e32 v186, v186
	v_mfma_f32_16x16x32_bf16 v[120:123], v[12:15], v[32:35], v[120:123]
	v_exp_f32_e32 v187, v187
	v_mfma_f32_16x16x32_bf16 v[136:139], v[12:15], v[44:47], v[136:139]
	v_exp_f32_e32 v200, v200
	v_mfma_f32_16x16x32_bf16 v[120:123], v[20:23], v[36:39], v[120:123]
	v_exp_f32_e32 v201, v201
	v_mfma_f32_16x16x32_bf16 v[136:139], v[20:23], v[16:19], v[136:139]
	v_exp_f32_e32 v202, v202
	v_exp_f32_e32 v203, v203
	ds_read_b128 v[4:7], v175 offset:2048
	ds_read_b128 v[12:15], v175 offset:6144
	ds_read_b128 v[20:23], v175 offset:10240
	ds_read_b64_tr_b16 v[208:209], v167 offset:36864
	ds_read_b64_tr_b16 v[210:211], v167 offset:38912
	ds_read_b64_tr_b16 v[240:241], v171 offset:36864
	ds_read_b64_tr_b16 v[242:243], v171 offset:38912
	ds_read_b64_tr_b16 v[252:253], v172 offset:36864
	ds_read_b64_tr_b16 v[254:255], v172 offset:38912
	v_mfma_f32_16x16x32_bf16 v[104:107], v[248:251], v[176:179], v[104:107]
	v_exp_f32_e32 v188, v188
	v_mfma_f32_16x16x32_bf16 v[88:91], v[248:251], v[192:195], v[88:91]
	v_exp_f32_e32 v189, v189
	v_mfma_f32_16x16x32_bf16 v[100:103], v[24:27], v[176:179], v[100:103]
	v_exp_f32_e32 v190, v190
	v_mfma_f32_16x16x32_bf16 v[80:83], v[24:27], v[192:195], v[80:83]
	v_exp_f32_e32 v191, v191
	v_mfma_f32_16x16x32_bf16 v[96:99], v[28:31], v[176:179], v[96:99]
	v_exp_f32_e32 v204, v204
	v_mfma_f32_16x16x32_bf16 v[76:79], v[28:31], v[192:195], v[76:79]
	v_exp_f32_e32 v205, v205
	v_mfma_f32_16x16x32_bf16 v[92:95], v[148:151], v[176:179], v[92:95]
	v_exp_f32_e32 v206, v206
	v_mfma_f32_16x16x32_bf16 v[72:75], v[148:151], v[192:195], v[72:75]
	v_exp_f32_e32 v207, v207
	v_mfma_f32_16x16x32_bf16 v[84:87], v[152:155], v[176:179], v[84:87]
	v_mfma_f32_16x16x32_bf16 v[68:71], v[152:155], v[192:195], v[68:71]
	s_waitcnt lgkmcnt(6)
	v_mfma_f32_16x16x32_bf16 v[124:127], v[4:7], v[8:11], v[108:111]
	v_cvt_pk_bf16_f32 v184, v184, v185
	v_cvt_pk_bf16_f32 v185, v186, v187
	v_mfma_f32_16x16x32_bf16 v[140:143], v[4:7], v[40:43], v[112:115]
	v_cvt_pk_bf16_f32 v186, v188, v189
	v_cvt_pk_bf16_f32 v187, v190, v191
	v_mfma_f32_16x16x32_bf16 v[124:127], v[12:15], v[32:35], v[124:127]
	v_cvt_pk_bf16_f32 v200, v200, v201
	v_cvt_pk_bf16_f32 v201, v202, v203
	v_mfma_f32_16x16x32_bf16 v[140:143], v[12:15], v[44:47], v[140:143]
	v_cvt_pk_bf16_f32 v202, v204, v205
	v_cvt_pk_bf16_f32 v203, v206, v207
	v_mfma_f32_16x16x32_bf16 v[124:127], v[20:23], v[36:39], v[124:127]
	v_mfma_f32_16x16x32_bf16 v[140:143], v[20:23], v[16:19], v[140:143]
	ds_read_b128 v[4:7], v175 offset:3072
	ds_read_b128 v[12:15], v175 offset:7168
	ds_read_b128 v[20:23], v175 offset:11264
	ds_read_b64_tr_b16 v[24:25], v173 offset:36864
	ds_read_b64_tr_b16 v[26:27], v173 offset:38912
	s_waitcnt lgkmcnt(5)
	v_mfma_f32_16x16x32_bf16 v[104:107], v[248:251], v[184:187], v[104:107]
	v_mfma_f32_16x16x32_bf16 v[88:91], v[248:251], v[200:203], v[88:91]
	v_mfma_f32_16x16x32_bf16 v[100:103], v[208:211], v[184:187], v[100:103]
	v_mfma_f32_16x16x32_bf16 v[80:83], v[208:211], v[200:203], v[80:83]
	v_mfma_f32_16x16x32_bf16 v[96:99], v[240:243], v[184:187], v[96:99]
	v_mfma_f32_16x16x32_bf16 v[76:79], v[240:243], v[200:203], v[76:79]
	v_mfma_f32_16x16x32_bf16 v[92:95], v[252:255], v[184:187], v[92:95]
	v_mfma_f32_16x16x32_bf16 v[72:75], v[252:255], v[200:203], v[72:75]
	s_waitcnt lgkmcnt(2)
	v_mfma_f32_16x16x32_bf16 v[128:131], v[4:7], v[8:11], v[108:111]
	v_mfma_f32_16x16x32_bf16 v[144:147], v[4:7], v[40:43], v[112:115]
	v_mfma_f32_16x16x32_bf16 v[128:131], v[12:15], v[32:35], v[128:131]
	v_mfma_f32_16x16x32_bf16 v[144:147], v[12:15], v[44:47], v[144:147]
	v_mfma_f32_16x16x32_bf16 v[128:131], v[20:23], v[36:39], v[128:131]
	v_mfma_f32_16x16x32_bf16 v[144:147], v[20:23], v[16:19], v[144:147]
	s_waitcnt lgkmcnt(0)
	v_mfma_f32_16x16x32_bf16 v[84:87], v[24:27], v[184:187], v[84:87]
	v_mfma_f32_16x16x32_bf16 v[68:71], v[24:27], v[200:203], v[68:71]
	s_add_i32 s57, s57, 1
	s_cmp_lt_u32 s57, s44
	s_barrier
	s_cbranch_scc1 .Lmla_x_body0

.Lmla_x_rare0:
	s_nop 7
	v_mov_b32_e32 v212, v2
	v_mov_b32_e32 v213, v3
	s_nop 1
	v_permlane16_swap_b32_e32 v2, v212
	v_permlane16_swap_b32_e32 v3, v213
	v_max_f32_e32 v2, v2, v212
	v_max_f32_e32 v3, v3, v213
	v_mov_b32_e32 v212, v2
	v_mov_b32_e32 v213, v3
	s_nop 1
	v_permlane32_swap_b32_e32 v2, v212
	v_permlane32_swap_b32_e32 v3, v213
	v_max_f32_e32 v2, v2, v212
	v_max_f32_e32 v3, v3, v213
	v_cmp_lt_f32_e32 vcc, s77, v2
	s_or_b64 vcc, s[0:1], vcc
	s_nop 1
	v_cndmask_b32_e32 v2, 0, v2, vcc
	v_exp_f32_e64 v212, -v2
	v_add_f32_e32 v0, v0, v2
	s_nop 0
	v_pk_mul_f32 v[104:105], v[104:105], v[212:213] op_sel_hi:[1,0]
	v_pk_mul_f32 v[106:107], v[106:107], v[212:213] op_sel_hi:[1,0]
	v_pk_mul_f32 v[100:101], v[100:101], v[212:213] op_sel_hi:[1,0]
	v_pk_mul_f32 v[102:103], v[102:103], v[212:213] op_sel_hi:[1,0]
	v_pk_mul_f32 v[96:97], v[96:97], v[212:213] op_sel_hi:[1,0]
	v_pk_mul_f32 v[98:99], v[98:99], v[212:213] op_sel_hi:[1,0]
	v_pk_mul_f32 v[92:93], v[92:93], v[212:213] op_sel_hi:[1,0]
	v_pk_mul_f32 v[94:95], v[94:95], v[212:213] op_sel_hi:[1,0]
	v_pk_mul_f32 v[84:85], v[84:85], v[212:213] op_sel_hi:[1,0]
	v_pk_mul_f32 v[86:87], v[86:87], v[212:213] op_sel_hi:[1,0]
	v_xor_b32_e32 v108, 0x80000000, v0
	v_mov_b32_e32 v109, v108
	v_mov_b32_e32 v110, v108
	v_mov_b32_e32 v111, v108
	v_sub_f32_e32 v116, v116, v2
	v_sub_f32_e32 v117, v117, v2
	v_sub_f32_e32 v118, v118, v2
	v_sub_f32_e32 v119, v119, v2
	v_sub_f32_e32 v120, v120, v2
	v_sub_f32_e32 v121, v121, v2
	v_sub_f32_e32 v122, v122, v2
	v_sub_f32_e32 v123, v123, v2
	v_sub_f32_e32 v124, v124, v2
	v_sub_f32_e32 v125, v125, v2
	v_sub_f32_e32 v126, v126, v2
	v_sub_f32_e32 v127, v127, v2
	v_sub_f32_e32 v128, v128, v2
	v_sub_f32_e32 v129, v129, v2
	v_sub_f32_e32 v130, v130, v2
	v_sub_f32_e32 v131, v131, v2
	v_cmp_lt_f32_e32 vcc, s77, v3
	s_or_b64 vcc, s[0:1], vcc
	s_nop 1
	v_cndmask_b32_e32 v3, 0, v3, vcc
	v_exp_f32_e64 v212, -v3
	v_add_f32_e32 v174, v174, v3
	s_nop 0
	v_pk_mul_f32 v[88:89], v[88:89], v[212:213] op_sel_hi:[1,0]
	v_pk_mul_f32 v[90:91], v[90:91], v[212:213] op_sel_hi:[1,0]
	v_pk_mul_f32 v[80:81], v[80:81], v[212:213] op_sel_hi:[1,0]
	v_pk_mul_f32 v[82:83], v[82:83], v[212:213] op_sel_hi:[1,0]
	v_pk_mul_f32 v[76:77], v[76:77], v[212:213] op_sel_hi:[1,0]
	v_pk_mul_f32 v[78:79], v[78:79], v[212:213] op_sel_hi:[1,0]
	v_pk_mul_f32 v[72:73], v[72:73], v[212:213] op_sel_hi:[1,0]
	v_pk_mul_f32 v[74:75], v[74:75], v[212:213] op_sel_hi:[1,0]
	v_pk_mul_f32 v[68:69], v[68:69], v[212:213] op_sel_hi:[1,0]
	v_pk_mul_f32 v[70:71], v[70:71], v[212:213] op_sel_hi:[1,0]
	v_xor_b32_e32 v112, 0x80000000, v174
	v_mov_b32_e32 v113, v112
	v_mov_b32_e32 v114, v112
	v_mov_b32_e32 v115, v112
	v_sub_f32_e32 v132, v132, v3
	v_sub_f32_e32 v133, v133, v3
	v_sub_f32_e32 v134, v134, v3
	v_sub_f32_e32 v135, v135, v3
	v_sub_f32_e32 v136, v136, v3
	v_sub_f32_e32 v137, v137, v3
	v_sub_f32_e32 v138, v138, v3
	v_sub_f32_e32 v139, v139, v3
	v_sub_f32_e32 v140, v140, v3
	v_sub_f32_e32 v141, v141, v3
	v_sub_f32_e32 v142, v142, v3
	v_sub_f32_e32 v143, v143, v3
	v_sub_f32_e32 v144, v144, v3
	v_sub_f32_e32 v145, v145, v3
	v_sub_f32_e32 v146, v146, v3
	v_sub_f32_e32 v147, v147, v3
	s_nop 1
	s_branch .Lmla_x_cont0
.Lmla_x_rare1:
	s_nop 7
	v_mov_b32_e32 v212, v2
	v_mov_b32_e32 v213, v3
	s_nop 1
	v_permlane16_swap_b32_e32 v2, v212
	v_permlane16_swap_b32_e32 v3, v213
	v_max_f32_e32 v2, v2, v212
	v_max_f32_e32 v3, v3, v213
	v_mov_b32_e32 v212, v2
	v_mov_b32_e32 v213, v3
	s_nop 1
	v_permlane32_swap_b32_e32 v2, v212
	v_permlane32_swap_b32_e32 v3, v213
	v_max_f32_e32 v2, v2, v212
	v_max_f32_e32 v3, v3, v213
	v_cmp_lt_f32_e32 vcc, s77, v2
	s_or_b64 vcc, s[0:1], vcc
	s_nop 1
	v_cndmask_b32_e32 v2, 0, v2, vcc
	v_exp_f32_e64 v212, -v2
	v_add_f32_e32 v0, v0, v2
	s_nop 0
	v_pk_mul_f32 v[104:105], v[104:105], v[212:213] op_sel_hi:[1,0]
	v_pk_mul_f32 v[106:107], v[106:107], v[212:213] op_sel_hi:[1,0]
	v_pk_mul_f32 v[100:101], v[100:101], v[212:213] op_sel_hi:[1,0]
	v_pk_mul_f32 v[102:103], v[102:103], v[212:213] op_sel_hi:[1,0]
	v_pk_mul_f32 v[96:97], v[96:97], v[212:213] op_sel_hi:[1,0]
	v_pk_mul_f32 v[98:99], v[98:99], v[212:213] op_sel_hi:[1,0]
	v_pk_mul_f32 v[92:93], v[92:93], v[212:213] op_sel_hi:[1,0]
	v_pk_mul_f32 v[94:95], v[94:95], v[212:213] op_sel_hi:[1,0]
	v_pk_mul_f32 v[84:85], v[84:85], v[212:213] op_sel_hi:[1,0]
	v_pk_mul_f32 v[86:87], v[86:87], v[212:213] op_sel_hi:[1,0]
	v_xor_b32_e32 v108, 0x80000000, v0
	v_mov_b32_e32 v109, v108
	v_mov_b32_e32 v110, v108
	v_mov_b32_e32 v111, v108
	v_sub_f32_e32 v176, v176, v2
	v_sub_f32_e32 v177, v177, v2
	v_sub_f32_e32 v178, v178, v2
	v_sub_f32_e32 v179, v179, v2
	v_sub_f32_e32 v180, v180, v2
	v_sub_f32_e32 v181, v181, v2
	v_sub_f32_e32 v182, v182, v2
	v_sub_f32_e32 v183, v183, v2
	v_sub_f32_e32 v184, v184, v2
	v_sub_f32_e32 v185, v185, v2
	v_sub_f32_e32 v186, v186, v2
	v_sub_f32_e32 v187, v187, v2
	v_sub_f32_e32 v188, v188, v2
	v_sub_f32_e32 v189, v189, v2
	v_sub_f32_e32 v190, v190, v2
	v_sub_f32_e32 v191, v191, v2
	v_cmp_lt_f32_e32 vcc, s77, v3
	s_or_b64 vcc, s[0:1], vcc
	s_nop 1
	v_cndmask_b32_e32 v3, 0, v3, vcc
	v_exp_f32_e64 v212, -v3
	v_add_f32_e32 v174, v174, v3
	s_nop 0
	v_pk_mul_f32 v[88:89], v[88:89], v[212:213] op_sel_hi:[1,0]
	v_pk_mul_f32 v[90:91], v[90:91], v[212:213] op_sel_hi:[1,0]
	v_pk_mul_f32 v[80:81], v[80:81], v[212:213] op_sel_hi:[1,0]
	v_pk_mul_f32 v[82:83], v[82:83], v[212:213] op_sel_hi:[1,0]
	v_pk_mul_f32 v[76:77], v[76:77], v[212:213] op_sel_hi:[1,0]
	v_pk_mul_f32 v[78:79], v[78:79], v[212:213] op_sel_hi:[1,0]
	v_pk_mul_f32 v[72:73], v[72:73], v[212:213] op_sel_hi:[1,0]
	v_pk_mul_f32 v[74:75], v[74:75], v[212:213] op_sel_hi:[1,0]
	v_pk_mul_f32 v[68:69], v[68:69], v[212:213] op_sel_hi:[1,0]
	v_pk_mul_f32 v[70:71], v[70:71], v[212:213] op_sel_hi:[1,0]
	v_xor_b32_e32 v112, 0x80000000, v174
	v_mov_b32_e32 v113, v112
	v_mov_b32_e32 v114, v112
	v_mov_b32_e32 v115, v112
	v_sub_f32_e32 v192, v192, v3
	v_sub_f32_e32 v193, v193, v3
	v_sub_f32_e32 v194, v194, v3
	v_sub_f32_e32 v195, v195, v3
	v_sub_f32_e32 v196, v196, v3
	v_sub_f32_e32 v197, v197, v3
	v_sub_f32_e32 v198, v198, v3
	v_sub_f32_e32 v199, v199, v3
	v_sub_f32_e32 v200, v200, v3
	v_sub_f32_e32 v201, v201, v3
	v_sub_f32_e32 v202, v202, v3
	v_sub_f32_e32 v203, v203, v3
	v_sub_f32_e32 v204, v204, v3
	v_sub_f32_e32 v205, v205, v3
	v_sub_f32_e32 v206, v206, v3
	v_sub_f32_e32 v207, v207, v3
	s_nop 1
	s_branch .Lmla_x_cont1

	.amdhsa_kernel _Z11mega_kernel6Paramsii
		.amdhsa_group_segment_fixed_size 66064
		.amdhsa_private_segment_fixed_size 0
		.amdhsa_kernarg_size 456
		.amdhsa_user_sgpr_count 2
		.amdhsa_user_sgpr_dispatch_ptr 0
		.amdhsa_user_sgpr_queue_ptr 0
		.amdhsa_user_sgpr_kernarg_segment_ptr 1
		.amdhsa_user_sgpr_dispatch_id 0
		.amdhsa_user_sgpr_kernarg_preload_length 0
		.amdhsa_user_sgpr_kernarg_preload_offset 0
		.amdhsa_user_sgpr_private_segment_size 0
		.amdhsa_uses_dynamic_stack 0
		.amdhsa_enable_private_segment 0
		.amdhsa_system_sgpr_workgroup_id_x 1
		.amdhsa_system_sgpr_workgroup_id_y 0
		.amdhsa_system_sgpr_workgroup_id_z 0
		.amdhsa_system_sgpr_workgroup_info 0
		.amdhsa_system_vgpr_workitem_id 2
		.amdhsa_next_free_vgpr 256
		.amdhsa_next_free_sgpr 100
		.amdhsa_accum_offset 256
		.amdhsa_reserve_vcc 1
		.amdhsa_float_round_mode_32 0
		.amdhsa_float_round_mode_16_64 0
		.amdhsa_float_denorm_mode_32 3
		.amdhsa_float_denorm_mode_16_64 3
		.amdhsa_dx10_clamp 1
		.amdhsa_ieee_mode 1
		.amdhsa_fp16_overflow 0
		.amdhsa_tg_split 0
		.amdhsa_exception_fp_ieee_invalid_op 0
		.amdhsa_exception_fp_denorm_src 0
		.amdhsa_exception_fp_ieee_div_zero 0
		.amdhsa_exception_fp_ieee_overflow 0
		.amdhsa_exception_fp_ieee_underflow 0
		.amdhsa_exception_fp_ieee_inexact 0
		.amdhsa_exception_int_div_zero 0
	.end_amdhsa_kernel

.Lfunc_end0:
	.size	_Z11mega_kernel6Paramsii, .Lfunc_end0-_Z11mega_kernel6Paramsii
	.set _Z11mega_kernel6Paramsii.num_vgpr, 256
	.set _Z11mega_kernel6Paramsii.num_agpr, 0
	.set _Z11mega_kernel6Paramsii.numbered_sgpr, 100
	.set _Z11mega_kernel6Paramsii.num_named_barrier, 0
	.set _Z11mega_kernel6Paramsii.private_seg_size, 0
	.set _Z11mega_kernel6Paramsii.uses_vcc, 1
	.set _Z11mega_kernel6Paramsii.uses_flat_scratch, 0
	.set _Z11mega_kernel6Paramsii.has_dyn_sized_stack, 0
	.set _Z11mega_kernel6Paramsii.has_recursion, 0
	.set _Z11mega_kernel6Paramsii.has_indirect_call, 0

amdhsa.kernels:
  - .agpr_count:     0
    .args:
      - .offset:         0
        .size:           192
        .value_kind:     by_value
      - .offset:         192
        .size:           4
        .value_kind:     by_value
      - .offset:         196
        .size:           4
        .value_kind:     by_value
      - .offset:         200
        .size:           4
        .value_kind:     hidden_block_count_x
      - .offset:         204
        .size:           4
        .value_kind:     hidden_block_count_y
      - .offset:         208
        .size:           4
        .value_kind:     hidden_block_count_z
      - .offset:         212
        .size:           2
        .value_kind:     hidden_group_size_x
      - .offset:         214
        .size:           2
        .value_kind:     hidden_group_size_y
      - .offset:         216
        .size:           2
        .value_kind:     hidden_group_size_z
      - .offset:         218
        .size:           2
        .value_kind:     hidden_remainder_x
      - .offset:         220
        .size:           2
        .value_kind:     hidden_remainder_y
      - .offset:         222
        .size:           2
        .value_kind:     hidden_remainder_z
      - .offset:         240
        .size:           8
        .value_kind:     hidden_global_offset_x
      - .offset:         248
        .size:           8
        .value_kind:     hidden_global_offset_y
      - .offset:         256
        .size:           8
        .value_kind:     hidden_global_offset_z
      - .offset:         264
        .size:           2
        .value_kind:     hidden_grid_dims
      - .offset:         288
        .size:           8
        .value_kind:     hidden_multigrid_sync_arg
    .group_segment_fixed_size: 66064
    .kernarg_segment_align: 8
    .kernarg_segment_size: 456
    .language:       OpenCL C
    .language_version:
      - 2
      - 0
    .max_flat_workgroup_size: 256
    .name:           _Z11mega_kernel6Paramsii
    .private_segment_fixed_size: 0
    .sgpr_count:     106
    .sgpr_spill_count: 281
    .symbol:         _Z11mega_kernel6Paramsii.kd
    .uniform_work_group_size: 1
    .uses_dynamic_stack: false
    .vgpr_count:     256
    .vgpr_spill_count: 0
    .wavefront_size: 64
